# plus: gate-up epilogue store addresses advanced by a constant instead of a 64-bit multiply-add per row group
# baseline (speedup 1.0000x reference)
.LBB0_830:
	s_mov_b32 s8, 0x16000
	s_mov_b32 s9, 0
	s_mov_b32 s56, 0x6e000
	s_mov_b32 s57, 0
	s_lshl_b32 s4, s30, 8
	v_mov_b32_e32 v66, v162
	v_mov_b32_e32 v67, v163
	s_add_i32 s4, s4, s25
	s_nop 0
	v_add_u32_e32 v158, s4, v66
	s_sub_i32 s4, s30, 32
	s_lshr_b32 s4, s4, 3
	s_mulk_i32 s4, 0x1600
	s_addk_i32 s4, 0x1600
	s_cmp_gt_i32 s30, 31
	s_cselect_b32 s30, s4, 0
	s_lshl_b64 s[4:5], s[30:31], 2
	s_add_u32 s6, s3, s4
	s_addc_u32 s7, s12, s5
	s_lshl_b32 s4, s2, 8
	s_ashr_i32 s5, s4, 31
	s_lshl_b64 s[4:5], s[4:5], 2
	s_add_u32 s4, s6, s4
	s_addc_u32 s5, s7, s5
	v_lshlrev_b32_e32 v156, 3, v67
	s_add_u32 s4, s4, s54
	s_addc_u32 s5, s5, 0
	v_ashrrev_i32_e32 v157, 31, v156
	v_ashrrev_i32_e32 v159, 31, v158
	v_lshl_add_u64 v[70:71], v[156:157], 2, s[4:5]
	v_lshl_add_u64 v[160:161], v[158:159], 2, s[42:43]
	global_load_dwordx4 v[74:77], v[70:71], off offset:16
	global_load_dwordx4 v[78:81], v[70:71], off
	global_load_dwordx4 v[66:69], v[70:71], off offset:528
	s_nop 0
	global_load_dwordx4 v[70:73], v[70:71], off offset:512
	s_lshl_b32 s2, s2, 7
	global_load_dword v157, v[160:161], off
	global_load_dword v179, v[160:161], off offset:64
	global_load_dword v177, v[160:161], off offset:128
	global_load_dword v175, v[160:161], off offset:192
	global_load_dword v173, v[160:161], off offset:512
	global_load_dword v171, v[160:161], off offset:576
	global_load_dword v169, v[160:161], off offset:640
	global_load_dword v167, v[160:161], off offset:704
	s_or_b32 s2, s2, s26
	v_add_u32_e32 v160, s2, v156
	v_ashrrev_i32_e32 v161, 31, v160
	s_movk_i32 s2, 0x1600
	s_waitcnt vmcnt(0)
	v_mul_f32_e32 v74, 0x3fb8aa3b, v74
	v_mul_f32_e32 v75, 0x3fb8aa3b, v75
	v_mul_f32_e32 v76, 0x3fb8aa3b, v76
	v_mul_f32_e32 v77, 0x3fb8aa3b, v77
	v_mul_f32_e32 v78, 0x3fb8aa3b, v78
	v_mul_f32_e32 v79, 0x3fb8aa3b, v79
	v_mul_f32_e32 v80, 0x3fb8aa3b, v80
	v_mul_f32_e32 v81, 0x3fb8aa3b, v81
	v_mul_f32_e32 v66, 0x3f317218, v66
	v_mul_f32_e32 v67, 0x3f317218, v67
	v_mul_f32_e32 v68, 0x3f317218, v68
	v_mul_f32_e32 v69, 0x3f317218, v69
	v_mul_f32_e32 v70, 0x3f317218, v70
	v_mul_f32_e32 v71, 0x3f317218, v71
	v_mul_f32_e32 v72, 0x3f317218, v72
	v_mul_f32_e32 v73, 0x3f317218, v73
	v_fmamk_f32 v156, v157, 0x3a800000, v202
	s_nop 0
	v_rsq_f32_e32 v156, v156
	s_nop 0
	v_mul_f32_e32 v184, 0x3fb8aa3b, v156
	v_mul_f32_e32 v186, 0x3f317218, v156
	v_mov_b64_e32 v[156:157], s[40:41]
	v_mad_i64_i32 v[182:183], s[4:5], v158, s2, v[156:157]
	v_lshlrev_b64 v[158:159], 1, v[160:161]
	v_pk_fma_f32 v[142:143], v[142:143], v[184:185], v[78:79] op_sel_hi:[1,0,1]
	v_lshl_add_u64 v[160:161], v[182:183], 0, v[158:159]
	v_pk_fma_f32 v[182:183], v[134:135], v[186:187], v[70:71] op_sel_hi:[1,0,1]
	v_pk_fma_f32 v[134:135], v[132:133], v[186:187], v[68:69] op_sel_hi:[1,0,1]
	v_pk_fma_f32 v[132:133], v[130:131], v[186:187], v[66:67] op_sel_hi:[1,0,1]
	v_exp_f32_e64 v130, -v142
	v_exp_f32_e64 v131, -v143
	v_pk_fma_f32 v[144:145], v[144:145], v[184:185], v[80:81] op_sel_hi:[1,0,1]
	v_pk_fma_f32 v[136:137], v[136:137], v[186:187], v[72:73] op_sel_hi:[1,0,1]
	v_add_f32_e32 v130, 1.0, v130
	v_add_f32_e32 v131, 1.0, v131
	v_rcp_f32_e32 v130, v130
	v_rcp_f32_e32 v131, v131
	v_pk_fma_f32 v[138:139], v[138:139], v[184:185], v[74:75] op_sel_hi:[1,0,1]
	v_pk_fma_f32 v[140:141], v[140:141], v[184:185], v[76:77] op_sel_hi:[1,0,1]
	v_pk_mul_f32 v[130:131], v[142:143], v[130:131]
	s_nop 0
	v_pk_mul_f32 v[130:131], v[182:183], v[130:131]
	s_nop 0
	v_cvt_pk_bf16_f32 v130, v130, v131
	v_exp_f32_e64 v131, -v144
	s_nop 0
	v_add_f32_e32 v131, 1.0, v131
	v_rcp_f32_e32 v142, v131
	v_exp_f32_e64 v131, -v145
	s_nop 0
	v_add_f32_e32 v131, 1.0, v131
	v_rcp_f32_e32 v143, v131
	s_nop 0
	v_pk_mul_f32 v[142:143], v[144:145], v[142:143]
	s_nop 0
	v_pk_mul_f32 v[136:137], v[136:137], v[142:143]
	s_nop 0
	v_cvt_pk_bf16_f32 v131, v136, v137
	v_exp_f32_e64 v136, -v138
	v_exp_f32_e64 v137, -v139
	v_add_f32_e32 v136, 1.0, v136
	v_add_f32_e32 v137, 1.0, v137
	v_rcp_f32_e32 v136, v136
	v_rcp_f32_e32 v137, v137
	s_nop 0
	v_pk_mul_f32 v[136:137], v[138:139], v[136:137]
	s_nop 0
	v_pk_mul_f32 v[132:133], v[132:133], v[136:137]
	s_nop 0
	v_cvt_pk_bf16_f32 v132, v132, v133
	v_exp_f32_e64 v133, -v140
	s_nop 0
	v_add_f32_e32 v133, 1.0, v133
	v_rcp_f32_e32 v136, v133
	v_exp_f32_e64 v133, -v141
	s_nop 0
	v_add_f32_e32 v133, 1.0, v133
	v_rcp_f32_e32 v137, v133
	s_nop 0
	v_pk_mul_f32 v[136:137], v[140:141], v[136:137]
	s_nop 0
	v_pk_mul_f32 v[134:135], v[134:135], v[136:137]
	s_nop 0
	v_cvt_pk_bf16_f32 v133, v134, v135
	global_store_dwordx4 v[160:161], v[130:133], off
	s_nop 1
	v_fmamk_f32 v130, v179, 0x3a800000, v202
	v_rsq_f32_e32 v130, v130
	v_lshl_add_u64 v[132:133], v[160:161], 0, s[8:9]
	v_mul_f32_e32 v184, 0x3fb8aa3b, v130
	v_mul_f32_e32 v186, 0x3f317218, v130
	v_pk_fma_f32 v[126:127], v[126:127], v[184:185], v[78:79] op_sel_hi:[1,0,1]
	v_pk_fma_f32 v[134:135], v[116:117], v[186:187], v[68:69] op_sel_hi:[1,0,1]
	v_pk_fma_f32 v[116:117], v[114:115], v[186:187], v[66:67] op_sel_hi:[1,0,1]
	v_exp_f32_e64 v114, -v126
	v_exp_f32_e64 v115, -v127
	v_pk_fma_f32 v[118:119], v[118:119], v[186:187], v[70:71] op_sel_hi:[1,0,1]
	v_pk_fma_f32 v[128:129], v[128:129], v[184:185], v[80:81] op_sel_hi:[1,0,1]
	v_add_f32_e32 v114, 1.0, v114
	v_add_f32_e32 v115, 1.0, v115
	v_rcp_f32_e32 v114, v114
	v_rcp_f32_e32 v115, v115
	v_pk_fma_f32 v[120:121], v[120:121], v[186:187], v[72:73] op_sel_hi:[1,0,1]
	v_pk_fma_f32 v[122:123], v[122:123], v[184:185], v[74:75] op_sel_hi:[1,0,1]
	v_pk_fma_f32 v[124:125], v[124:125], v[184:185], v[76:77] op_sel_hi:[1,0,1]
	v_pk_mul_f32 v[114:115], v[126:127], v[114:115]
	s_nop 0
	v_pk_mul_f32 v[114:115], v[118:119], v[114:115]
	s_nop 0
	v_cvt_pk_bf16_f32 v114, v114, v115
	v_exp_f32_e64 v115, -v128
	s_nop 0
	v_add_f32_e32 v115, 1.0, v115
	v_rcp_f32_e32 v118, v115
	v_exp_f32_e64 v115, -v129
	s_nop 0
	v_add_f32_e32 v115, 1.0, v115
	v_rcp_f32_e32 v119, v115
	s_nop 0
	v_pk_mul_f32 v[118:119], v[128:129], v[118:119]
	s_nop 0
	v_pk_mul_f32 v[118:119], v[120:121], v[118:119]
	s_nop 0
	v_cvt_pk_bf16_f32 v115, v118, v119
	v_exp_f32_e64 v118, -v122
	v_exp_f32_e64 v119, -v123
	v_add_f32_e32 v118, 1.0, v118
	v_add_f32_e32 v119, 1.0, v119
	v_rcp_f32_e32 v118, v118
	v_rcp_f32_e32 v119, v119
	s_nop 0
	v_pk_mul_f32 v[118:119], v[122:123], v[118:119]
	s_nop 0
	v_pk_mul_f32 v[116:117], v[116:117], v[118:119]
	s_nop 0
	v_cvt_pk_bf16_f32 v116, v116, v117
	v_exp_f32_e64 v117, -v124
	s_nop 0
	v_add_f32_e32 v117, 1.0, v117
	v_rcp_f32_e32 v118, v117
	v_exp_f32_e64 v117, -v125
	s_nop 0
	v_add_f32_e32 v117, 1.0, v117
	v_rcp_f32_e32 v119, v117
	s_nop 0
	v_pk_mul_f32 v[118:119], v[124:125], v[118:119]
	s_nop 0
	v_pk_mul_f32 v[118:119], v[134:135], v[118:119]
	s_nop 0
	v_cvt_pk_bf16_f32 v117, v118, v119
	global_store_dwordx4 v[132:133], v[114:117], off
	s_nop 1
	v_fmamk_f32 v114, v177, 0x3a800000, v202
	v_rsq_f32_e32 v114, v114
	v_lshl_add_u64 v[116:117], v[132:133], 0, s[8:9]
	v_mul_f32_e32 v184, 0x3fb8aa3b, v114
	v_mul_f32_e32 v186, 0x3f317218, v114
	v_pk_fma_f32 v[110:111], v[110:111], v[184:185], v[78:79] op_sel_hi:[1,0,1]
	v_pk_fma_f32 v[118:119], v[100:101], v[186:187], v[68:69] op_sel_hi:[1,0,1]
	v_pk_fma_f32 v[100:101], v[98:99], v[186:187], v[66:67] op_sel_hi:[1,0,1]
	v_exp_f32_e64 v98, -v110
	v_exp_f32_e64 v99, -v111
	v_pk_fma_f32 v[102:103], v[102:103], v[186:187], v[70:71] op_sel_hi:[1,0,1]
	v_pk_fma_f32 v[112:113], v[112:113], v[184:185], v[80:81] op_sel_hi:[1,0,1]
	v_add_f32_e32 v98, 1.0, v98
	v_add_f32_e32 v99, 1.0, v99
	v_rcp_f32_e32 v98, v98
	v_rcp_f32_e32 v99, v99
	v_pk_fma_f32 v[104:105], v[104:105], v[186:187], v[72:73] op_sel_hi:[1,0,1]
	v_pk_fma_f32 v[106:107], v[106:107], v[184:185], v[74:75] op_sel_hi:[1,0,1]
	v_pk_fma_f32 v[108:109], v[108:109], v[184:185], v[76:77] op_sel_hi:[1,0,1]
	v_pk_mul_f32 v[98:99], v[110:111], v[98:99]
	s_nop 0
	v_pk_mul_f32 v[98:99], v[102:103], v[98:99]
	s_nop 0
	v_cvt_pk_bf16_f32 v98, v98, v99
	v_exp_f32_e64 v99, -v112
	s_nop 0
	v_add_f32_e32 v99, 1.0, v99
	v_rcp_f32_e32 v102, v99
	v_exp_f32_e64 v99, -v113
	s_nop 0
	v_add_f32_e32 v99, 1.0, v99
	v_rcp_f32_e32 v103, v99
	s_nop 0
	v_pk_mul_f32 v[102:103], v[112:113], v[102:103]
	s_nop 0
	v_pk_mul_f32 v[102:103], v[104:105], v[102:103]
	s_nop 0
	v_cvt_pk_bf16_f32 v99, v102, v103
	v_exp_f32_e64 v102, -v106
	v_exp_f32_e64 v103, -v107
	v_add_f32_e32 v102, 1.0, v102
	v_add_f32_e32 v103, 1.0, v103
	v_rcp_f32_e32 v102, v102
	v_rcp_f32_e32 v103, v103
	s_nop 0
	v_pk_mul_f32 v[102:103], v[106:107], v[102:103]
	s_nop 0
	v_pk_mul_f32 v[100:101], v[100:101], v[102:103]
	s_nop 0
	v_cvt_pk_bf16_f32 v100, v100, v101
	v_exp_f32_e64 v101, -v108
	s_nop 0
	v_add_f32_e32 v101, 1.0, v101
	v_rcp_f32_e32 v102, v101
	v_exp_f32_e64 v101, -v109
	s_nop 0
	v_add_f32_e32 v101, 1.0, v101
	v_rcp_f32_e32 v103, v101
	s_nop 0
	v_pk_mul_f32 v[102:103], v[108:109], v[102:103]
	s_nop 0
	v_pk_mul_f32 v[102:103], v[118:119], v[102:103]
	s_nop 0
	v_cvt_pk_bf16_f32 v101, v102, v103
	global_store_dwordx4 v[116:117], v[98:101], off
	s_nop 1
	v_fmamk_f32 v98, v175, 0x3a800000, v202
	v_rsq_f32_e32 v98, v98
	v_lshl_add_u64 v[100:101], v[116:117], 0, s[8:9]
	v_mul_f32_e32 v184, 0x3fb8aa3b, v98
	v_mul_f32_e32 v186, 0x3f317218, v98
	v_pk_fma_f32 v[94:95], v[94:95], v[184:185], v[78:79] op_sel_hi:[1,0,1]
	v_pk_fma_f32 v[102:103], v[84:85], v[186:187], v[68:69] op_sel_hi:[1,0,1]
	v_pk_fma_f32 v[84:85], v[82:83], v[186:187], v[66:67] op_sel_hi:[1,0,1]
	v_exp_f32_e64 v82, -v94
	v_exp_f32_e64 v83, -v95
	v_pk_fma_f32 v[86:87], v[86:87], v[186:187], v[70:71] op_sel_hi:[1,0,1]
	v_pk_fma_f32 v[96:97], v[96:97], v[184:185], v[80:81] op_sel_hi:[1,0,1]
	v_add_f32_e32 v82, 1.0, v82
	v_add_f32_e32 v83, 1.0, v83
	v_rcp_f32_e32 v82, v82
	v_rcp_f32_e32 v83, v83
	v_pk_fma_f32 v[88:89], v[88:89], v[186:187], v[72:73] op_sel_hi:[1,0,1]
	v_pk_fma_f32 v[90:91], v[90:91], v[184:185], v[74:75] op_sel_hi:[1,0,1]
	v_pk_fma_f32 v[92:93], v[92:93], v[184:185], v[76:77] op_sel_hi:[1,0,1]
	v_pk_mul_f32 v[82:83], v[94:95], v[82:83]
	s_nop 0
	v_pk_mul_f32 v[82:83], v[86:87], v[82:83]
	s_nop 0
	v_cvt_pk_bf16_f32 v82, v82, v83
	v_exp_f32_e64 v83, -v96
	s_nop 0
	v_add_f32_e32 v83, 1.0, v83
	v_rcp_f32_e32 v86, v83
	v_exp_f32_e64 v83, -v97
	s_nop 0
	v_add_f32_e32 v83, 1.0, v83
	v_rcp_f32_e32 v87, v83
	s_nop 0
	v_pk_mul_f32 v[86:87], v[96:97], v[86:87]
	s_nop 0
	v_pk_mul_f32 v[86:87], v[88:89], v[86:87]
	s_nop 0
	v_cvt_pk_bf16_f32 v83, v86, v87
	v_exp_f32_e64 v86, -v90
	v_exp_f32_e64 v87, -v91
	v_add_f32_e32 v86, 1.0, v86
	v_add_f32_e32 v87, 1.0, v87
	v_rcp_f32_e32 v86, v86
	v_rcp_f32_e32 v87, v87
	s_nop 0
	v_pk_mul_f32 v[86:87], v[90:91], v[86:87]
	s_nop 0
	v_pk_mul_f32 v[84:85], v[84:85], v[86:87]
	s_nop 0
	v_cvt_pk_bf16_f32 v84, v84, v85
	v_exp_f32_e64 v85, -v92
	s_nop 0
	v_add_f32_e32 v85, 1.0, v85
	v_rcp_f32_e32 v86, v85
	v_exp_f32_e64 v85, -v93
	s_nop 0
	v_add_f32_e32 v85, 1.0, v85
	v_rcp_f32_e32 v87, v85
	s_nop 0
	v_pk_mul_f32 v[86:87], v[92:93], v[86:87]
	s_nop 0
	v_pk_mul_f32 v[86:87], v[102:103], v[86:87]
	s_nop 0
	v_cvt_pk_bf16_f32 v85, v86, v87
	global_store_dwordx4 v[100:101], v[82:85], off
	s_nop 1
	v_fmamk_f32 v82, v173, 0x3a800000, v202
	v_rsq_f32_e32 v82, v82
	v_lshl_add_u64 v[84:85], v[100:101], 0, s[56:57]
	v_mul_f32_e32 v184, 0x3fb8aa3b, v82
	v_mul_f32_e32 v186, 0x3f317218, v82
	v_pk_fma_f32 v[62:63], v[62:63], v[184:185], v[78:79] op_sel_hi:[1,0,1]
	v_pk_fma_f32 v[86:87], v[52:53], v[186:187], v[68:69] op_sel_hi:[1,0,1]
	v_pk_fma_f32 v[52:53], v[50:51], v[186:187], v[66:67] op_sel_hi:[1,0,1]
	v_exp_f32_e64 v50, -v62
	v_exp_f32_e64 v51, -v63
	v_pk_fma_f32 v[54:55], v[54:55], v[186:187], v[70:71] op_sel_hi:[1,0,1]
	v_pk_fma_f32 v[64:65], v[64:65], v[184:185], v[80:81] op_sel_hi:[1,0,1]
	v_add_f32_e32 v50, 1.0, v50
	v_add_f32_e32 v51, 1.0, v51
	v_rcp_f32_e32 v50, v50
	v_rcp_f32_e32 v51, v51
	v_pk_fma_f32 v[56:57], v[56:57], v[186:187], v[72:73] op_sel_hi:[1,0,1]
	v_pk_fma_f32 v[58:59], v[58:59], v[184:185], v[74:75] op_sel_hi:[1,0,1]
	v_pk_fma_f32 v[60:61], v[60:61], v[184:185], v[76:77] op_sel_hi:[1,0,1]
	v_pk_mul_f32 v[50:51], v[62:63], v[50:51]
	s_nop 0
	v_pk_mul_f32 v[50:51], v[54:55], v[50:51]
	s_nop 0
	v_cvt_pk_bf16_f32 v50, v50, v51
	v_exp_f32_e64 v51, -v64
	s_nop 0
	v_add_f32_e32 v51, 1.0, v51
	v_rcp_f32_e32 v54, v51
	v_exp_f32_e64 v51, -v65
	s_nop 0
	v_add_f32_e32 v51, 1.0, v51
	v_rcp_f32_e32 v55, v51
	s_nop 0
	v_pk_mul_f32 v[54:55], v[64:65], v[54:55]
	s_nop 0
	v_pk_mul_f32 v[54:55], v[56:57], v[54:55]
	s_nop 0
	v_cvt_pk_bf16_f32 v51, v54, v55
	v_exp_f32_e64 v54, -v58
	v_exp_f32_e64 v55, -v59
	v_add_f32_e32 v54, 1.0, v54
	v_add_f32_e32 v55, 1.0, v55
	v_rcp_f32_e32 v54, v54
	v_rcp_f32_e32 v55, v55
	s_nop 0
	v_pk_mul_f32 v[54:55], v[58:59], v[54:55]
	s_nop 0
	v_pk_mul_f32 v[52:53], v[52:53], v[54:55]
	s_nop 0
	v_cvt_pk_bf16_f32 v52, v52, v53
	v_exp_f32_e64 v53, -v60
	s_nop 0
	v_add_f32_e32 v53, 1.0, v53
	v_rcp_f32_e32 v54, v53
	v_exp_f32_e64 v53, -v61
	s_nop 0
	v_add_f32_e32 v53, 1.0, v53
	v_rcp_f32_e32 v55, v53
	s_nop 0
	v_pk_mul_f32 v[54:55], v[60:61], v[54:55]
	s_nop 0
	v_pk_mul_f32 v[54:55], v[86:87], v[54:55]
	s_nop 0
	v_cvt_pk_bf16_f32 v53, v54, v55
	global_store_dwordx4 v[84:85], v[50:53], off
	s_nop 1
	v_fmamk_f32 v50, v171, 0x3a800000, v202
	v_rsq_f32_e32 v50, v50
	v_lshl_add_u64 v[52:53], v[84:85], 0, s[8:9]
	v_mul_f32_e32 v184, 0x3fb8aa3b, v50
	v_mul_f32_e32 v186, 0x3f317218, v50
	v_pk_fma_f32 v[46:47], v[46:47], v[184:185], v[78:79] op_sel_hi:[1,0,1]
	v_pk_fma_f32 v[54:55], v[36:37], v[186:187], v[68:69] op_sel_hi:[1,0,1]
	v_pk_fma_f32 v[36:37], v[34:35], v[186:187], v[66:67] op_sel_hi:[1,0,1]
	v_exp_f32_e64 v34, -v46
	v_exp_f32_e64 v35, -v47
	v_pk_fma_f32 v[38:39], v[38:39], v[186:187], v[70:71] op_sel_hi:[1,0,1]
	v_pk_fma_f32 v[48:49], v[48:49], v[184:185], v[80:81] op_sel_hi:[1,0,1]
	v_add_f32_e32 v34, 1.0, v34
	v_add_f32_e32 v35, 1.0, v35
	v_rcp_f32_e32 v34, v34
	v_rcp_f32_e32 v35, v35
	v_pk_fma_f32 v[40:41], v[40:41], v[186:187], v[72:73] op_sel_hi:[1,0,1]
	v_pk_fma_f32 v[42:43], v[42:43], v[184:185], v[74:75] op_sel_hi:[1,0,1]
	v_pk_fma_f32 v[44:45], v[44:45], v[184:185], v[76:77] op_sel_hi:[1,0,1]
	v_pk_mul_f32 v[34:35], v[46:47], v[34:35]
	s_nop 0
	v_pk_mul_f32 v[34:35], v[38:39], v[34:35]
	s_nop 0
	v_cvt_pk_bf16_f32 v34, v34, v35
	v_exp_f32_e64 v35, -v48
	s_nop 0
	v_add_f32_e32 v35, 1.0, v35
	v_rcp_f32_e32 v38, v35
	v_exp_f32_e64 v35, -v49
	s_nop 0
	v_add_f32_e32 v35, 1.0, v35
	v_rcp_f32_e32 v39, v35
	s_nop 0
	v_pk_mul_f32 v[38:39], v[48:49], v[38:39]
	s_nop 0
	v_pk_mul_f32 v[38:39], v[40:41], v[38:39]
	s_nop 0
	v_cvt_pk_bf16_f32 v35, v38, v39
	v_exp_f32_e64 v38, -v42
	v_exp_f32_e64 v39, -v43
	v_add_f32_e32 v38, 1.0, v38
	v_add_f32_e32 v39, 1.0, v39
	v_rcp_f32_e32 v38, v38
	v_rcp_f32_e32 v39, v39
	s_nop 0
	v_pk_mul_f32 v[38:39], v[42:43], v[38:39]
	s_nop 0
	v_pk_mul_f32 v[36:37], v[36:37], v[38:39]
	s_nop 0
	v_cvt_pk_bf16_f32 v36, v36, v37
	v_exp_f32_e64 v37, -v44
	s_nop 0
	v_add_f32_e32 v37, 1.0, v37
	v_rcp_f32_e32 v38, v37
	v_exp_f32_e64 v37, -v45
	s_nop 0
	v_add_f32_e32 v37, 1.0, v37
	v_rcp_f32_e32 v39, v37
	s_nop 0
	v_pk_mul_f32 v[38:39], v[44:45], v[38:39]
	s_nop 0
	v_pk_mul_f32 v[38:39], v[54:55], v[38:39]
	s_nop 0
	v_cvt_pk_bf16_f32 v37, v38, v39
	global_store_dwordx4 v[52:53], v[34:37], off
	s_nop 1
	v_fmamk_f32 v34, v169, 0x3a800000, v202
	v_rsq_f32_e32 v34, v34
	v_lshl_add_u64 v[36:37], v[52:53], 0, s[8:9]
	v_mul_f32_e32 v184, 0x3fb8aa3b, v34
	v_mul_f32_e32 v186, 0x3f317218, v34
	v_pk_fma_f32 v[30:31], v[30:31], v[184:185], v[78:79] op_sel_hi:[1,0,1]
	v_pk_fma_f32 v[38:39], v[20:21], v[186:187], v[68:69] op_sel_hi:[1,0,1]
	v_pk_fma_f32 v[20:21], v[18:19], v[186:187], v[66:67] op_sel_hi:[1,0,1]
	v_exp_f32_e64 v18, -v30
	v_exp_f32_e64 v19, -v31
	v_pk_fma_f32 v[22:23], v[22:23], v[186:187], v[70:71] op_sel_hi:[1,0,1]
	v_pk_fma_f32 v[32:33], v[32:33], v[184:185], v[80:81] op_sel_hi:[1,0,1]
	v_add_f32_e32 v18, 1.0, v18
	v_add_f32_e32 v19, 1.0, v19
	v_rcp_f32_e32 v18, v18
	v_rcp_f32_e32 v19, v19
	v_pk_fma_f32 v[24:25], v[24:25], v[186:187], v[72:73] op_sel_hi:[1,0,1]
	v_pk_fma_f32 v[26:27], v[26:27], v[184:185], v[74:75] op_sel_hi:[1,0,1]
	v_pk_fma_f32 v[28:29], v[28:29], v[184:185], v[76:77] op_sel_hi:[1,0,1]
	v_pk_mul_f32 v[18:19], v[30:31], v[18:19]
	s_nop 0
	v_pk_mul_f32 v[18:19], v[22:23], v[18:19]
	s_nop 0
	v_cvt_pk_bf16_f32 v18, v18, v19
	v_exp_f32_e64 v19, -v32
	s_nop 0
	v_add_f32_e32 v19, 1.0, v19
	v_rcp_f32_e32 v22, v19
	v_exp_f32_e64 v19, -v33
	s_nop 0
	v_add_f32_e32 v19, 1.0, v19
	v_rcp_f32_e32 v23, v19
	s_nop 0
	v_pk_mul_f32 v[22:23], v[32:33], v[22:23]
	s_nop 0
	v_pk_mul_f32 v[22:23], v[24:25], v[22:23]
	s_nop 0
	v_cvt_pk_bf16_f32 v19, v22, v23
	v_exp_f32_e64 v22, -v26
	v_exp_f32_e64 v23, -v27
	v_add_f32_e32 v22, 1.0, v22
	v_add_f32_e32 v23, 1.0, v23
	v_rcp_f32_e32 v22, v22
	v_rcp_f32_e32 v23, v23
	s_nop 0
	v_pk_mul_f32 v[22:23], v[26:27], v[22:23]
	s_nop 0
	v_pk_mul_f32 v[20:21], v[20:21], v[22:23]
	s_nop 0
	v_cvt_pk_bf16_f32 v20, v20, v21
	v_exp_f32_e64 v21, -v28
	s_nop 0
	v_add_f32_e32 v21, 1.0, v21
	v_rcp_f32_e32 v22, v21
	v_exp_f32_e64 v21, -v29
	s_nop 0
	v_add_f32_e32 v21, 1.0, v21
	v_rcp_f32_e32 v23, v21
	s_nop 0
	v_pk_mul_f32 v[22:23], v[28:29], v[22:23]
	s_nop 0
	v_pk_mul_f32 v[22:23], v[38:39], v[22:23]
	s_nop 0
	v_cvt_pk_bf16_f32 v21, v22, v23
	global_store_dwordx4 v[36:37], v[18:21], off
	s_nop 1
	v_fmamk_f32 v18, v167, 0x3a800000, v202
	v_rsq_f32_e32 v18, v18
	v_lshl_add_u64 v[20:21], v[36:37], 0, s[8:9]
	v_mul_f32_e32 v184, 0x3fb8aa3b, v18
	v_mul_f32_e32 v186, 0x3f317218, v18
	v_pk_fma_f32 v[14:15], v[14:15], v[184:185], v[78:79] op_sel_hi:[1,0,1]
	v_pk_fma_f32 v[22:23], v[4:5], v[186:187], v[68:69] op_sel_hi:[1,0,1]
	v_pk_fma_f32 v[4:5], v[2:3], v[186:187], v[66:67] op_sel_hi:[1,0,1]
	v_exp_f32_e64 v2, -v14
	v_exp_f32_e64 v3, -v15
	v_pk_fma_f32 v[6:7], v[6:7], v[186:187], v[70:71] op_sel_hi:[1,0,1]
	v_pk_fma_f32 v[16:17], v[16:17], v[184:185], v[80:81] op_sel_hi:[1,0,1]
	v_add_f32_e32 v2, 1.0, v2
	v_add_f32_e32 v3, 1.0, v3
	v_rcp_f32_e32 v2, v2
	v_rcp_f32_e32 v3, v3
	v_pk_fma_f32 v[8:9], v[8:9], v[186:187], v[72:73] op_sel_hi:[1,0,1]
	v_pk_fma_f32 v[10:11], v[10:11], v[184:185], v[74:75] op_sel_hi:[1,0,1]
	v_pk_fma_f32 v[12:13], v[12:13], v[184:185], v[76:77] op_sel_hi:[1,0,1]
	v_pk_mul_f32 v[2:3], v[14:15], v[2:3]
	s_nop 0
	v_pk_mul_f32 v[2:3], v[6:7], v[2:3]
	s_nop 0
	v_cvt_pk_bf16_f32 v2, v2, v3
	v_exp_f32_e64 v3, -v16
	s_nop 0
	v_add_f32_e32 v3, 1.0, v3
	v_rcp_f32_e32 v6, v3
	v_exp_f32_e64 v3, -v17
	s_nop 0
	v_add_f32_e32 v3, 1.0, v3
	v_rcp_f32_e32 v7, v3
	s_nop 0
	v_pk_mul_f32 v[6:7], v[16:17], v[6:7]
	s_nop 0
	v_pk_mul_f32 v[6:7], v[8:9], v[6:7]
	s_nop 0
	v_cvt_pk_bf16_f32 v3, v6, v7
	v_exp_f32_e64 v6, -v10
	v_exp_f32_e64 v7, -v11
	v_add_f32_e32 v6, 1.0, v6
	v_add_f32_e32 v7, 1.0, v7
	v_rcp_f32_e32 v6, v6
	v_rcp_f32_e32 v7, v7
	s_nop 0
	v_pk_mul_f32 v[6:7], v[10:11], v[6:7]
	s_nop 0
	v_pk_mul_f32 v[4:5], v[4:5], v[6:7]
	s_nop 0
	v_cvt_pk_bf16_f32 v4, v4, v5
	v_exp_f32_e64 v5, -v12
	s_nop 0
	v_add_f32_e32 v5, 1.0, v5
	v_rcp_f32_e32 v6, v5
	v_exp_f32_e64 v5, -v13
	s_nop 0
	v_add_f32_e32 v5, 1.0, v5
	v_rcp_f32_e32 v7, v5
	s_nop 0
	v_pk_mul_f32 v[6:7], v[12:13], v[6:7]
	s_nop 0
	v_pk_mul_f32 v[6:7], v[22:23], v[6:7]
	s_nop 0
	v_cvt_pk_bf16_f32 v5, v6, v7
	global_store_dwordx4 v[20:21], v[2:5], off
	s_andn2_b64 vcc, exec, s[34:35]
	s_mov_b64 s[4:5], -1
	s_cbranch_vccnz .LBB0_821
	s_andn2_b64 vcc, exec, s[38:39]
	s_cbranch_vccnz .LBB0_820
	s_barrier
	s_branch .LBB0_820
